# merge GEMM (3 passes per tile): first two k-phase waits after an epilogue no longer drain the epilogue's trailing stores (vmcnt 40)
# baseline (speedup 1.0000x reference)
.LBB0_779:
	s_add_i32 m0, s23, 0x18000
	v_lshl_add_u64 v[8:9], v[8:9], 0, s[62:63]
	s_waitcnt vmcnt(2)
	s_barrier
	global_load_lds_dwordx4 v[8:9], off
	v_lshl_add_u64 v[8:9], v[10:11], 0, s[62:63]
	s_add_i32 m0, s23, 0x1a000
	s_add_i32 s27, s23, 0x8000
	global_load_lds_dwordx4 v[8:9], off
	v_lshl_add_u64 v[8:9], v[12:13], 0, s[62:63]
	s_mov_b32 m0, s27
	s_add_i32 s28, s23, 0xa000
	global_load_lds_dwordx4 v[8:9], off
	v_lshl_add_u64 v[8:9], v[14:15], 0, s[62:63]
	s_mov_b32 m0, s28
	s_mov_b64 s[12:13], 0x8b89000
	global_load_lds_dwordx4 v[8:9], off
	v_lshl_add_u64 v[8:9], v[2:3], 0, s[54:55]
	s_add_i32 m0, s23, 0x1c000
	v_lshl_add_u64 v[10:11], v[8:9], 0, v[0:1]
	global_load_lds_dwordx4 v[10:11], off
	v_lshl_add_u64 v[8:9], v[8:9], 0, v[204:205]
	s_add_i32 m0, s23, 0x1e000
	v_lshl_add_u64 v[210:211], v[6:7], 0, s[12:13]
	global_load_lds_dwordx4 v[8:9], off
	s_mov_b64 s[12:13], 0x12b89000
	v_lshl_add_u64 v[212:213], v[6:7], 0, s[12:13]
	v_lshrrev_b32_e32 v7, 1, v16
	v_and_b32_e32 v7, 24, v7
	v_and_b32_e32 v6, 15, v16
	v_lshlrev_b32_e32 v8, 1, v7
	v_lshl_or_b32 v252, s6, 6, v6
	v_lshl_or_b32 v6, v6, 6, v8
	v_lshlrev_b32_e32 v8, 2, v16
	s_lshl_b32 s5, s5, 5
	s_lshl_b32 s6, s6, 13
	v_and_b32_e32 v8, 32, v8
	s_and_b32 s5, s5, 0x60
	v_bitop3_b32 v9, v6, s6, v8 bitop3:0xde
	s_lshl_b32 s6, s5, 7
	v_bitop3_b32 v253, v6, s6, v8 bitop3:0xde
	v_lshlrev_b32_e32 v6, 13, v17
	v_and_b32_e32 v6, 0xffffc000, v6
	v_or_b32_e32 v245, s5, v7
	v_lshl_add_u32 v6, v18, 10, v6
	v_and_b32_e32 v7, 1, v17
	v_lshl_or_b32 v6, v7, 6, v6
	v_lshl_add_u32 v214, v19, 1, v6
	v_lshlrev_b32_e32 v6, 13, v21
	v_and_b32_e32 v6, 0xffffc000, v6
	s_waitcnt vmcnt(6)
	v_lshl_add_u32 v6, v20, 10, v6
	v_and_b32_e32 v7, 1, v21
	s_cmpk_lt_u32 s4, 0x100
	v_lshl_or_b32 v6, v7, 6, v6
	v_readlane_b32 s4, v254, 47
	s_cselect_b64 s[12:13], -1, 0
	v_mov_b32_e32 v215, v1
	v_lshl_add_u32 v216, v22, 1, v6
	v_mov_b32_e32 v217, v1
	s_mov_b32 s30, 0
	v_add_u32_e32 v242, 0, v9
	v_readlane_b32 s20, v254, 25
	s_mov_b32 s21, s4
	s_mov_b32 s29, 0
	s_barrier
	v_readlane_b32 s5, v254, 48
	s_mov_b32 s98, 0
	s_branch .LBB0_782

.LBB0_781:
	s_mov_b32 s98, 1
	s_andn2_b64 vcc, exec, s[4:5]
	s_mov_b32 s30, s16
	s_mov_b32 s20, s14
	s_mov_b32 s21, s18
	v_mov_b64_e32 v[2:3], v[220:221]
	v_mov_b64_e32 v[4:5], v[218:219]
	s_cbranch_vccz .LBB0_829

.LBB0_789:
	s_cmp_eq_u32 s6, 4
	s_cselect_b64 vcc, -1, 0
	s_add_i32 s7, 0, 0x10000
	s_add_i32 s15, 0, 0x14000
	v_add_u32_e32 v150, s7, v253
	v_add_u32_e32 v166, s15, v253
	ds_read_b128 v[138:141], v150
	ds_read_b128 v[142:145], v150 offset:1024
	ds_read_b128 v[146:149], v150 offset:2048
	ds_read_b128 v[150:153], v150 offset:3072
	ds_read_b128 v[154:157], v166
	ds_read_b128 v[158:161], v166 offset:1024
	ds_read_b128 v[162:165], v166 offset:2048
	ds_read_b128 v[166:169], v166 offset:3072
	s_mov_b32 s34, 0xfffe0080
	s_mov_b32 s35, -1
	v_lshl_add_u64 v[170:171], v[136:137], 0, s[34:35]
	v_cndmask_b32_e32 v195, v171, v131, vcc
	v_cndmask_b32_e32 v194, v170, v130, vcc
	v_cndmask_b32_e32 v231, v135, v133, vcc
	v_cndmask_b32_e32 v230, v134, v132, vcc
	v_lshl_add_u64 v[232:233], v[136:137], 0, v[216:217]
	s_add_i32 m0, s23, 0xc000
	ds_read_b128 v[170:173], v242
	ds_read_b128 v[174:177], v242 offset:1024
	ds_read_b128 v[178:181], v242 offset:2048
	ds_read_b128 v[182:185], v242 offset:3072
	ds_read_b128 v[186:189], v242 offset:4096
	ds_read_b128 v[190:193], v242 offset:5120
	ds_read_b128 v[222:225], v242 offset:6144
	ds_read_b128 v[226:229], v242 offset:7168
	global_load_lds_dwordx4 v[232:233], off
	v_lshl_add_u64 v[232:233], v[136:137], 0, v[214:215]
	s_add_i32 m0, s23, 0xe000
	s_nop 0
	global_load_lds_dwordx4 v[232:233], off
	s_cmp_lg_u32 s98, 0
	s_cbranch_scc1 .Lgr_g6_1
	s_waitcnt vmcnt(8)
.Lgr_g6_1:
	s_waitcnt vmcnt(40)
	s_waitcnt lgkmcnt(0)
	s_barrier
	s_setprio 1
	s_waitcnt lgkmcnt(0)
	v_mfma_f32_16x16x32_bf16 v[126:129], v[138:141], v[170:173], v[126:129]
	v_mfma_f32_16x16x32_bf16 v[122:125], v[146:149], v[170:173], v[122:125]
	v_mfma_f32_16x16x32_bf16 v[110:113], v[138:141], v[178:181], v[110:113]
	v_mfma_f32_16x16x32_bf16 v[106:109], v[146:149], v[178:181], v[106:109]
	v_mfma_f32_16x16x32_bf16 v[102:105], v[138:141], v[186:189], v[102:105]
	v_mfma_f32_16x16x32_bf16 v[98:101], v[146:149], v[186:189], v[98:101]
	v_mfma_f32_16x16x32_bf16 v[94:97], v[138:141], v[222:225], v[94:97]
	v_mfma_f32_16x16x32_bf16 v[90:93], v[146:149], v[222:225], v[90:93]
	v_mfma_f32_16x16x32_bf16 v[126:129], v[142:145], v[174:177], v[126:129]
	v_mfma_f32_16x16x32_bf16 v[122:125], v[150:153], v[174:177], v[122:125]
	v_mfma_f32_16x16x32_bf16 v[110:113], v[142:145], v[182:185], v[110:113]
	v_mfma_f32_16x16x32_bf16 v[106:109], v[150:153], v[182:185], v[106:109]
	v_mfma_f32_16x16x32_bf16 v[102:105], v[142:145], v[190:193], v[102:105]
	v_mfma_f32_16x16x32_bf16 v[98:101], v[150:153], v[190:193], v[98:101]
	v_mfma_f32_16x16x32_bf16 v[94:97], v[142:145], v[226:229], v[94:97]
	v_mfma_f32_16x16x32_bf16 v[90:93], v[150:153], v[226:229], v[90:93]
	s_setprio 0
	s_setprio 1
	v_mfma_f32_16x16x32_bf16 v[118:121], v[154:157], v[170:173], v[118:121]
	v_mfma_f32_16x16x32_bf16 v[114:117], v[162:165], v[170:173], v[114:117]
	v_mfma_f32_16x16x32_bf16 v[86:89], v[154:157], v[178:181], v[86:89]
	v_mfma_f32_16x16x32_bf16 v[82:85], v[162:165], v[178:181], v[82:85]
	v_mfma_f32_16x16x32_bf16 v[78:81], v[154:157], v[186:189], v[78:81]
	v_mfma_f32_16x16x32_bf16 v[74:77], v[162:165], v[186:189], v[74:77]
	v_mfma_f32_16x16x32_bf16 v[70:73], v[154:157], v[222:225], v[70:73]
	v_mfma_f32_16x16x32_bf16 v[66:69], v[162:165], v[222:225], v[66:69]
	v_mfma_f32_16x16x32_bf16 v[118:121], v[158:161], v[174:177], v[118:121]
	v_mfma_f32_16x16x32_bf16 v[114:117], v[166:169], v[174:177], v[114:117]
	v_mfma_f32_16x16x32_bf16 v[86:89], v[158:161], v[182:185], v[86:89]
	v_mfma_f32_16x16x32_bf16 v[82:85], v[166:169], v[182:185], v[82:85]
	v_mfma_f32_16x16x32_bf16 v[78:81], v[158:161], v[190:193], v[78:81]
	v_mfma_f32_16x16x32_bf16 v[74:77], v[166:169], v[190:193], v[74:77]
	v_mfma_f32_16x16x32_bf16 v[70:73], v[158:161], v[226:229], v[70:73]
	v_mfma_f32_16x16x32_bf16 v[66:69], v[166:169], v[226:229], v[66:69]
	s_setprio 0
	s_barrier
	s_add_i32 s7, s7, s22
	v_lshl_add_u64 v[232:233], v[230:231], 0, v[0:1]
	s_mov_b32 m0, s7
	ds_read_b128 v[170:173], v242 offset:16384
	ds_read_b128 v[174:177], v242 offset:17408
	ds_read_b128 v[178:181], v242 offset:18432
	ds_read_b128 v[182:185], v242 offset:19456
	ds_read_b128 v[186:189], v242 offset:20480
	ds_read_b128 v[190:193], v242 offset:21504
	ds_read_b128 v[222:225], v242 offset:22528
	ds_read_b128 v[226:229], v242 offset:23552
	global_load_lds_dwordx4 v[232:233], off
	v_lshl_add_u64 v[234:235], v[230:231], 0, v[204:205]
	s_add_i32 m0, s7, 0x2000
	v_lshl_add_u64 v[236:237], v[230:231], 0, s[50:51]
	s_add_i32 s7, s15, s22
	global_load_lds_dwordx4 v[234:235], off
	v_lshl_add_u64 v[238:239], v[236:237], 0, v[0:1]
	s_mov_b32 m0, s7
	v_lshl_add_u64 v[236:237], v[236:237], 0, v[204:205]
	global_load_lds_dwordx4 v[238:239], off
	s_add_i32 m0, s7, 0x2000
	v_lshl_add_u64 v[238:239], v[194:195], 0, v[206:207]
	global_load_lds_dwordx4 v[236:237], off
	v_lshl_add_u64 v[236:237], v[194:195], 0, v[208:209]
	s_mov_b32 m0, s23
	s_nop 0
	global_load_lds_dwordx4 v[236:237], off
	s_mov_b32 m0, s24
	s_nop 0
	global_load_lds_dwordx4 v[238:239], off
	s_cmp_lg_u32 s98, 0
	s_cbranch_scc1 .Lgr_g6_2
	s_waitcnt vmcnt(8)
.Lgr_g6_2:
	s_waitcnt vmcnt(40)
	s_mov_b32 s98, 0
	s_waitcnt lgkmcnt(0)
	s_barrier
	s_setprio 1
	s_waitcnt lgkmcnt(0)
	v_mfma_f32_16x16x32_bf16 v[62:65], v[138:141], v[170:173], v[62:65]
	v_mfma_f32_16x16x32_bf16 v[58:61], v[146:149], v[170:173], v[58:61]
	v_mfma_f32_16x16x32_bf16 v[46:49], v[138:141], v[178:181], v[46:49]
	v_mfma_f32_16x16x32_bf16 v[42:45], v[146:149], v[178:181], v[42:45]
	v_mfma_f32_16x16x32_bf16 v[30:33], v[138:141], v[186:189], v[30:33]
	v_mfma_f32_16x16x32_bf16 v[26:29], v[146:149], v[186:189], v[26:29]
	v_mfma_f32_16x16x32_bf16 v[14:17], v[138:141], v[222:225], v[14:17]
	v_mfma_f32_16x16x32_bf16 v[10:13], v[146:149], v[222:225], v[10:13]
	v_mfma_f32_16x16x32_bf16 v[62:65], v[142:145], v[174:177], v[62:65]
	v_mfma_f32_16x16x32_bf16 v[58:61], v[150:153], v[174:177], v[58:61]
	v_mfma_f32_16x16x32_bf16 v[46:49], v[142:145], v[182:185], v[46:49]
	v_mfma_f32_16x16x32_bf16 v[42:45], v[150:153], v[182:185], v[42:45]
	v_mfma_f32_16x16x32_bf16 v[30:33], v[142:145], v[190:193], v[30:33]
	v_mfma_f32_16x16x32_bf16 v[26:29], v[150:153], v[190:193], v[26:29]
	v_mfma_f32_16x16x32_bf16 v[14:17], v[142:145], v[226:229], v[14:17]
	v_mfma_f32_16x16x32_bf16 v[10:13], v[150:153], v[226:229], v[10:13]
	s_setprio 0
	s_setprio 1
	v_mfma_f32_16x16x32_bf16 v[54:57], v[154:157], v[170:173], v[54:57]
	v_mfma_f32_16x16x32_bf16 v[50:53], v[162:165], v[170:173], v[50:53]
	v_mfma_f32_16x16x32_bf16 v[38:41], v[154:157], v[178:181], v[38:41]
	v_mfma_f32_16x16x32_bf16 v[34:37], v[162:165], v[178:181], v[34:37]
	v_mfma_f32_16x16x32_bf16 v[22:25], v[154:157], v[186:189], v[22:25]
	v_mfma_f32_16x16x32_bf16 v[18:21], v[162:165], v[186:189], v[18:21]
	v_mfma_f32_16x16x32_bf16 v[6:9], v[154:157], v[222:225], v[6:9]
	v_mfma_f32_16x16x32_bf16 v[2:5], v[162:165], v[222:225], v[2:5]
	v_mfma_f32_16x16x32_bf16 v[54:57], v[158:161], v[174:177], v[54:57]
	v_mfma_f32_16x16x32_bf16 v[50:53], v[166:169], v[174:177], v[50:53]
	v_mfma_f32_16x16x32_bf16 v[38:41], v[158:161], v[182:185], v[38:41]
	v_mfma_f32_16x16x32_bf16 v[34:37], v[166:169], v[182:185], v[34:37]
	v_mfma_f32_16x16x32_bf16 v[22:25], v[158:161], v[190:193], v[22:25]
	v_mfma_f32_16x16x32_bf16 v[18:21], v[166:169], v[190:193], v[18:21]
	v_mfma_f32_16x16x32_bf16 v[6:9], v[158:161], v[226:229], v[6:9]
	v_mfma_f32_16x16x32_bf16 v[2:5], v[166:169], v[226:229], v[2:5]
	s_setprio 0
	s_barrier
	s_add_i32 s7, 0, 0x18000
	s_add_i32 s15, 0, 0x1c000
	v_add_u32_e32 v150, s7, v253
	v_add_u32_e32 v166, s15, v253
	ds_read_b128 v[138:141], v150
	ds_read_b128 v[142:145], v150 offset:1024
	ds_read_b128 v[146:149], v150 offset:2048
	ds_read_b128 v[150:153], v150 offset:3072
	ds_read_b128 v[154:157], v166
	ds_read_b128 v[158:161], v166 offset:1024
	ds_read_b128 v[162:165], v166 offset:2048
	ds_read_b128 v[166:169], v166 offset:3072
	v_lshl_add_u64 v[194:195], v[194:195], 0, s[50:51]
	s_mov_b32 m0, s25
	v_lshl_add_u64 v[240:241], v[194:195], 0, v[208:209]
	ds_read_b128 v[170:173], v242 offset:32768
	ds_read_b128 v[174:177], v242 offset:33792
	ds_read_b128 v[178:181], v242 offset:34816
	ds_read_b128 v[182:185], v242 offset:35840
	ds_read_b128 v[186:189], v242 offset:36864
	ds_read_b128 v[190:193], v242 offset:37888
	ds_read_b128 v[222:225], v242 offset:38912
	ds_read_b128 v[226:229], v242 offset:39936
	global_load_lds_dwordx4 v[240:241], off
	v_lshl_add_u64 v[194:195], v[194:195], 0, v[206:207]
	s_mov_b32 m0, s26
	s_nop 0
	global_load_lds_dwordx4 v[194:195], off
	s_waitcnt vmcnt(8)
	s_waitcnt lgkmcnt(0)
	s_barrier
	s_setprio 1
	s_waitcnt lgkmcnt(0)
	v_mfma_f32_16x16x32_bf16 v[126:129], v[138:141], v[170:173], v[126:129]
	v_mfma_f32_16x16x32_bf16 v[122:125], v[146:149], v[170:173], v[122:125]
	v_mfma_f32_16x16x32_bf16 v[110:113], v[138:141], v[178:181], v[110:113]
	v_mfma_f32_16x16x32_bf16 v[106:109], v[146:149], v[178:181], v[106:109]
	v_mfma_f32_16x16x32_bf16 v[102:105], v[138:141], v[186:189], v[102:105]
	v_mfma_f32_16x16x32_bf16 v[98:101], v[146:149], v[186:189], v[98:101]
	v_mfma_f32_16x16x32_bf16 v[94:97], v[138:141], v[222:225], v[94:97]
	v_mfma_f32_16x16x32_bf16 v[90:93], v[146:149], v[222:225], v[90:93]
	v_mfma_f32_16x16x32_bf16 v[126:129], v[142:145], v[174:177], v[126:129]
	v_mfma_f32_16x16x32_bf16 v[122:125], v[150:153], v[174:177], v[122:125]
	v_mfma_f32_16x16x32_bf16 v[110:113], v[142:145], v[182:185], v[110:113]
	v_mfma_f32_16x16x32_bf16 v[106:109], v[150:153], v[182:185], v[106:109]
	v_mfma_f32_16x16x32_bf16 v[102:105], v[142:145], v[190:193], v[102:105]
	v_mfma_f32_16x16x32_bf16 v[98:101], v[150:153], v[190:193], v[98:101]
	v_mfma_f32_16x16x32_bf16 v[94:97], v[142:145], v[226:229], v[94:97]
	v_mfma_f32_16x16x32_bf16 v[90:93], v[150:153], v[226:229], v[90:93]
	s_setprio 0
	s_setprio 1
	v_mfma_f32_16x16x32_bf16 v[118:121], v[154:157], v[170:173], v[118:121]
	v_mfma_f32_16x16x32_bf16 v[114:117], v[162:165], v[170:173], v[114:117]
	v_mfma_f32_16x16x32_bf16 v[86:89], v[154:157], v[178:181], v[86:89]
	v_mfma_f32_16x16x32_bf16 v[82:85], v[162:165], v[178:181], v[82:85]
	v_mfma_f32_16x16x32_bf16 v[78:81], v[154:157], v[186:189], v[78:81]
	v_mfma_f32_16x16x32_bf16 v[74:77], v[162:165], v[186:189], v[74:77]
	v_mfma_f32_16x16x32_bf16 v[70:73], v[154:157], v[222:225], v[70:73]
	v_mfma_f32_16x16x32_bf16 v[66:69], v[162:165], v[222:225], v[66:69]
	v_mfma_f32_16x16x32_bf16 v[118:121], v[158:161], v[174:177], v[118:121]
	v_mfma_f32_16x16x32_bf16 v[114:117], v[166:169], v[174:177], v[114:117]
	v_mfma_f32_16x16x32_bf16 v[86:89], v[158:161], v[182:185], v[86:89]
	v_mfma_f32_16x16x32_bf16 v[82:85], v[166:169], v[182:185], v[82:85]
	v_mfma_f32_16x16x32_bf16 v[78:81], v[158:161], v[190:193], v[78:81]
	v_mfma_f32_16x16x32_bf16 v[74:77], v[166:169], v[190:193], v[74:77]
	v_mfma_f32_16x16x32_bf16 v[70:73], v[158:161], v[226:229], v[70:73]
	v_mfma_f32_16x16x32_bf16 v[66:69], v[166:169], v[226:229], v[66:69]
	s_setprio 0
	s_barrier
	s_add_i32 s7, s7, s22
	v_lshl_add_u64 v[194:195], v[232:233], 0, s[62:63]
	s_mov_b32 m0, s7
	ds_read_b128 v[170:173], v242 offset:49152
	ds_read_b128 v[174:177], v242 offset:50176
	ds_read_b128 v[178:181], v242 offset:51200
	ds_read_b128 v[182:185], v242 offset:52224
	ds_read_b128 v[186:189], v242 offset:53248
	ds_read_b128 v[190:193], v242 offset:54272
	ds_read_b128 v[222:225], v242 offset:55296
	ds_read_b128 v[226:229], v242 offset:56320
	global_load_lds_dwordx4 v[194:195], off
	v_lshl_add_u64 v[194:195], v[234:235], 0, s[62:63]
	s_add_i32 m0, s7, 0x2000
	s_add_i32 s7, s15, s22
	global_load_lds_dwordx4 v[194:195], off
	v_lshl_add_u64 v[194:195], v[230:231], 0, s[54:55]
	v_lshl_add_u64 v[230:231], v[194:195], 0, v[0:1]
	s_mov_b32 m0, s7
	v_lshl_add_u64 v[194:195], v[194:195], 0, v[204:205]
	global_load_lds_dwordx4 v[230:231], off
	s_add_i32 m0, s7, 0x2000
	s_nop 0
	global_load_lds_dwordx4 v[194:195], off
	v_lshl_add_u64 v[194:195], v[236:237], 0, s[62:63]
	s_mov_b32 m0, s27
	s_nop 0
	global_load_lds_dwordx4 v[194:195], off
	v_lshl_add_u64 v[194:195], v[238:239], 0, s[62:63]
	s_mov_b32 m0, s28
	s_nop 0
	global_load_lds_dwordx4 v[194:195], off
	s_waitcnt vmcnt(8)
	s_waitcnt lgkmcnt(0)
	s_barrier
	s_setprio 1
	s_waitcnt lgkmcnt(0)
	v_mfma_f32_16x16x32_bf16 v[62:65], v[138:141], v[170:173], v[62:65]
	v_mfma_f32_16x16x32_bf16 v[58:61], v[146:149], v[170:173], v[58:61]
	v_mfma_f32_16x16x32_bf16 v[46:49], v[138:141], v[178:181], v[46:49]
	v_mfma_f32_16x16x32_bf16 v[42:45], v[146:149], v[178:181], v[42:45]
	v_mfma_f32_16x16x32_bf16 v[30:33], v[138:141], v[186:189], v[30:33]
	v_mfma_f32_16x16x32_bf16 v[26:29], v[146:149], v[186:189], v[26:29]
	v_mfma_f32_16x16x32_bf16 v[14:17], v[138:141], v[222:225], v[14:17]
	v_mfma_f32_16x16x32_bf16 v[10:13], v[146:149], v[222:225], v[10:13]
	v_mfma_f32_16x16x32_bf16 v[62:65], v[142:145], v[174:177], v[62:65]
	v_mfma_f32_16x16x32_bf16 v[58:61], v[150:153], v[174:177], v[58:61]
	v_mfma_f32_16x16x32_bf16 v[46:49], v[142:145], v[182:185], v[46:49]
	v_mfma_f32_16x16x32_bf16 v[42:45], v[150:153], v[182:185], v[42:45]
	v_mfma_f32_16x16x32_bf16 v[30:33], v[142:145], v[190:193], v[30:33]
	v_mfma_f32_16x16x32_bf16 v[26:29], v[150:153], v[190:193], v[26:29]
	v_mfma_f32_16x16x32_bf16 v[14:17], v[142:145], v[226:229], v[14:17]
	v_mfma_f32_16x16x32_bf16 v[10:13], v[150:153], v[226:229], v[10:13]
	s_setprio 0
	s_setprio 1
	v_mfma_f32_16x16x32_bf16 v[54:57], v[154:157], v[170:173], v[54:57]
	v_mfma_f32_16x16x32_bf16 v[50:53], v[162:165], v[170:173], v[50:53]
	v_mfma_f32_16x16x32_bf16 v[38:41], v[154:157], v[178:181], v[38:41]
	v_mfma_f32_16x16x32_bf16 v[34:37], v[162:165], v[178:181], v[34:37]
	v_mfma_f32_16x16x32_bf16 v[22:25], v[154:157], v[186:189], v[22:25]
	v_mfma_f32_16x16x32_bf16 v[18:21], v[162:165], v[186:189], v[18:21]
	v_mfma_f32_16x16x32_bf16 v[6:9], v[154:157], v[222:225], v[6:9]
	v_mfma_f32_16x16x32_bf16 v[2:5], v[162:165], v[222:225], v[2:5]
	v_mfma_f32_16x16x32_bf16 v[54:57], v[158:161], v[174:177], v[54:57]
	v_mfma_f32_16x16x32_bf16 v[50:53], v[166:169], v[174:177], v[50:53]
	v_mfma_f32_16x16x32_bf16 v[38:41], v[158:161], v[182:185], v[38:41]
	v_mfma_f32_16x16x32_bf16 v[34:37], v[166:169], v[182:185], v[34:37]
	v_mfma_f32_16x16x32_bf16 v[22:25], v[158:161], v[190:193], v[22:25]
	v_mfma_f32_16x16x32_bf16 v[18:21], v[166:169], v[190:193], v[18:21]
	v_mfma_f32_16x16x32_bf16 v[6:9], v[158:161], v[226:229], v[6:9]
	v_mfma_f32_16x16x32_bf16 v[2:5], v[166:169], v[226:229], v[2:5]
	s_setprio 0
	s_barrier
	s_add_i32 s6, s6, 2
	v_lshl_add_u64 v[134:135], v[134:135], 0, s[86:87]
	s_cmp_gt_u32 s6, 5
	v_lshl_add_u64 v[136:137], v[136:137], 0, s[86:87]
	s_cbranch_scc0 .LBB0_789
	s_and_b64 vcc, exec, s[12:13]
	s_cbranch_vccz .LBB0_792
	s_barrier
